# G2 output accumulators kept transposed (MFMA operands swapped) so each lane stores 4 consecutive columns: 4 dwordx2 stores per step instead of 16 two-byte stores
# baseline (speedup 1.0000x reference)
.LBB0_563:
	v_lshlrev_b32_e32 v252, 4, v58
	s_and_b64 vcc, exec, s[6:7]
	s_cbranch_vccz .Lg2h_setup
	s_lshl_b32 s4, s83, 11
	s_add_u32 s28, s28, s4
	s_addc_u32 s29, s29, 0
	s_add_u32 s48, s92, s46
	s_addc_u32 s49, s93, s47
	s_lshl_b32 s4, s78, 3
	s_add_u32 s48, s48, s4
	s_addc_u32 s49, s49, 0
	s_add_u32 s48, s48, 0xdd20000
	s_addc_u32 s49, s49, 0
	s_add_u32 s36, s92, s36
	s_addc_u32 s37, s93, s37
	s_add_u32 s36, s36, 0x80000
	s_addc_u32 s37, s37, 0
	global_load_dword v236, v1, s[36:37]
	s_add_u32 s36, s36, 32
	s_addc_u32 s37, s37, 0
	s_mov_b32 s19, 0
	v_mov_b32_e32 v238, v252
	v_and_b32_e32 v250, 15, v58
	v_lshlrev_b32_e32 v250, 11, v250
	v_lshrrev_b32_e32 v251, 4, v58
	v_lshlrev_b32_e32 v251, 3, v251
	v_add_u32_e32 v239, v250, v251
	v_add_u32_e32 v240, 0x8000, v239
	v_add_u32_e32 v241, 0x10000, v239
	v_add_u32_e32 v246, 0x18000, v239
	v_lshlrev_b32_e32 v249, 3, v58
.Lg2c_loop:
	ds_read_b128 v[80:83], v238 offset:0
	ds_read_b128 v[84:87], v238 offset:4096
	ds_read_b128 v[88:91], v238 offset:8192
	ds_read_b128 v[92:95], v238 offset:12288
	ds_read_b128 v[96:99], v238 offset:16384
	ds_read_b128 v[100:103], v238 offset:20480
	ds_read_b128 v[104:107], v238 offset:24576
	ds_read_b128 v[108:111], v238 offset:28672
	ds_read_b128 v[112:115], v238 offset:1024
	ds_read_b128 v[116:119], v238 offset:5120
	ds_read_b128 v[120:123], v238 offset:9216
	ds_read_b128 v[124:127], v238 offset:13312
	ds_read_b128 v[128:131], v238 offset:17408
	ds_read_b128 v[132:135], v238 offset:21504
	ds_read_b128 v[136:139], v238 offset:25600
	ds_read_b128 v[140:143], v238 offset:29696
	s_cmp_eq_u32 s19, 0
	s_cbranch_scc1 .Lg2c_nost
	global_store_dwordx2 v239, v[78:79], s[28:29]
	global_store_dwordx2 v240, v[194:195], s[28:29]
	global_store_dwordx2 v241, v[254:255], s[28:29]
	global_store_dwordx2 v246, v[242:243], s[28:29]
	s_add_u32 s28, s28, 0x20000
	s_addc_u32 s29, s29, 0
.Lg2c_nost:
	v_cvt_pk_bf16_f32 v62, v4, v5
	v_cvt_pk_bf16_f32 v63, v6, v7
	v_cvt_pk_bf16_f32 v64, v8, v9
	v_cvt_pk_bf16_f32 v65, v10, v11
	s_waitcnt lgkmcnt(8)
	s_nop 0
	v_mfma_f32_16x16x32_bf16 v[176:179], v[80:83], v[62:65], 0
	ds_read_b128 v[144:147], v238 offset:2048
	ds_read_b128 v[148:151], v238 offset:6144
	ds_read_b128 v[152:155], v238 offset:10240
	v_mfma_f32_16x16x32_bf16 v[196:199], v[62:65], v[96:99], 0
	ds_read_b128 v[156:159], v238 offset:14336
	ds_read_b128 v[160:163], v238 offset:18432
	v_mfma_f32_16x16x32_bf16 v[180:183], v[84:87], v[62:65], 0
	ds_read_b128 v[164:167], v238 offset:22528
	ds_read_b128 v[168:171], v238 offset:26624
	ds_read_b128 v[172:175], v238 offset:30720
	v_mfma_f32_16x16x32_bf16 v[200:203], v[62:65], v[100:103], 0
	v_cvt_pk_bf16_f32 v66, v12, v13
	v_cvt_pk_bf16_f32 v67, v14, v15
	v_mfma_f32_16x16x32_bf16 v[184:187], v[88:91], v[62:65], 0
	v_cvt_pk_bf16_f32 v68, v16, v17
	v_cvt_pk_bf16_f32 v69, v18, v19
	v_cvt_pk_bf16_f32 v70, v20, v21
	v_mfma_f32_16x16x32_bf16 v[204:207], v[62:65], v[104:107], 0
	v_cvt_pk_bf16_f32 v71, v22, v23
	v_cvt_pk_bf16_f32 v72, v24, v25
	v_mfma_f32_16x16x32_bf16 v[188:191], v[92:95], v[62:65], 0
	v_cvt_pk_bf16_f32 v73, v26, v27
	v_cvt_pk_bf16_f32 v74, v28, v29
	v_cvt_pk_bf16_f32 v75, v30, v31
	v_mfma_f32_16x16x32_bf16 v[208:211], v[62:65], v[108:111], 0
	v_cvt_pk_bf16_f32 v76, v32, v33
	v_cvt_pk_bf16_f32 v77, v34, v35
	s_cmp_eq_u32 s19, 0
	s_cbranch_scc0 .Lg2c_w16
	s_waitcnt vmcnt(0)
.Lg2c_w16:
	s_waitcnt vmcnt(4)
	s_waitcnt lgkmcnt(8)
	v_mfma_f32_16x16x32_bf16 v[176:179], v[112:115], v[66:69], v[176:179]
	ds_read_b128 v[80:83], v238 offset:3072
	ds_read_b128 v[84:87], v238 offset:7168
	ds_read_b128 v[88:91], v238 offset:11264
	v_mfma_f32_16x16x32_bf16 v[196:199], v[66:69], v[128:131], v[196:199]
	ds_read_b128 v[92:95], v238 offset:15360
	ds_read_b128 v[96:99], v238 offset:19456
	ds_read_b128 v[100:103], v238 offset:23552
	v_mfma_f32_16x16x32_bf16 v[180:183], v[116:119], v[66:69], v[180:183]
	ds_read_b128 v[104:107], v238 offset:27648
	ds_read_b128 v[108:111], v238 offset:31744
	v_lshlrev_b32_e32 v212, 16, v50
	v_mfma_f32_16x16x32_bf16 v[200:203], v[66:69], v[132:135], v[200:203]
	v_and_b32_e32 v213, 0xffff0000, v50
	v_lshlrev_b32_e32 v214, 16, v51
	v_and_b32_e32 v215, 0xffff0000, v51
	v_mfma_f32_16x16x32_bf16 v[184:187], v[120:123], v[66:69], v[184:187]
	v_lshlrev_b32_e32 v216, 16, v52
	v_and_b32_e32 v217, 0xffff0000, v52
	v_lshlrev_b32_e32 v218, 16, v53
	v_mfma_f32_16x16x32_bf16 v[204:207], v[66:69], v[136:139], v[204:207]
	v_and_b32_e32 v219, 0xffff0000, v53
	v_lshlrev_b32_e32 v220, 16, v54
	v_and_b32_e32 v221, 0xffff0000, v54
	v_mfma_f32_16x16x32_bf16 v[188:191], v[124:127], v[66:69], v[188:191]
	v_lshlrev_b32_e32 v222, 16, v55
	v_and_b32_e32 v223, 0xffff0000, v55
	v_lshlrev_b32_e32 v224, 16, v56
	v_mfma_f32_16x16x32_bf16 v[208:211], v[66:69], v[140:143], v[208:211]
	v_and_b32_e32 v225, 0xffff0000, v56
	v_lshlrev_b32_e32 v226, 16, v57
	v_and_b32_e32 v227, 0xffff0000, v57
	s_waitcnt lgkmcnt(8)
	v_mfma_f32_16x16x32_bf16 v[176:179], v[144:147], v[70:73], v[176:179]
	v_pk_mul_f32 v[4:5], v[4:5], v[236:237] op_sel_hi:[1,0]
	v_pk_mul_f32 v[6:7], v[6:7], v[236:237] op_sel_hi:[1,0]
	v_mfma_f32_16x16x32_bf16 v[196:199], v[70:73], v[160:163], v[196:199]
	v_pk_mul_f32 v[8:9], v[8:9], v[236:237] op_sel_hi:[1,0]
	v_pk_mul_f32 v[10:11], v[10:11], v[236:237] op_sel_hi:[1,0]
	v_mfma_f32_16x16x32_bf16 v[180:183], v[148:151], v[70:73], v[180:183]
	v_pk_mul_f32 v[12:13], v[12:13], v[236:237] op_sel_hi:[1,0]
	v_pk_mul_f32 v[14:15], v[14:15], v[236:237] op_sel_hi:[1,0]
	v_mfma_f32_16x16x32_bf16 v[200:203], v[70:73], v[164:167], v[200:203]
	v_pk_mul_f32 v[16:17], v[16:17], v[236:237] op_sel_hi:[1,0]
	v_pk_mul_f32 v[18:19], v[18:19], v[236:237] op_sel_hi:[1,0]
	v_mfma_f32_16x16x32_bf16 v[184:187], v[152:155], v[70:73], v[184:187]
	v_pk_mul_f32 v[20:21], v[20:21], v[236:237] op_sel_hi:[1,0]
	v_pk_mul_f32 v[22:23], v[22:23], v[236:237] op_sel_hi:[1,0]
	v_mfma_f32_16x16x32_bf16 v[204:207], v[70:73], v[168:171], v[204:207]
	v_pk_mul_f32 v[24:25], v[24:25], v[236:237] op_sel_hi:[1,0]
	v_pk_mul_f32 v[26:27], v[26:27], v[236:237] op_sel_hi:[1,0]
	v_mfma_f32_16x16x32_bf16 v[188:191], v[156:159], v[70:73], v[188:191]
	v_pk_mul_f32 v[28:29], v[28:29], v[236:237] op_sel_hi:[1,0]
	v_pk_mul_f32 v[30:31], v[30:31], v[236:237] op_sel_hi:[1,0]
	v_mfma_f32_16x16x32_bf16 v[208:211], v[70:73], v[172:175], v[208:211]
	v_pk_mul_f32 v[32:33], v[32:33], v[236:237] op_sel_hi:[1,0]
	v_pk_mul_f32 v[34:35], v[34:35], v[236:237] op_sel_hi:[1,0]
	s_cmp_lt_u32 s19, 31
	s_cbranch_scc0 .Lg2c_noload
	global_load_dword v236, v1, s[36:37]
	global_load_dwordx2 v[50:51], v249, s[48:49] offset:0
	global_load_dwordx2 v[52:53], v249, s[48:49] offset:512
	global_load_dwordx2 v[54:55], v249, s[48:49] offset:1024
	global_load_dwordx2 v[56:57], v249, s[48:49] offset:1536
.Lg2c_noload:
	s_waitcnt lgkmcnt(0)
	s_barrier
	v_mfma_f32_16x16x32_bf16 v[176:179], v[80:83], v[74:77], v[176:179]
	ds_read_b128 v[112:115], v238 offset:32768
	ds_read_b128 v[116:119], v238 offset:34816
	ds_read_b128 v[120:123], v238 offset:36864
	ds_read_b128 v[124:127], v238 offset:38912
	v_mfma_f32_16x16x32_bf16 v[180:183], v[84:87], v[74:77], v[180:183]
	ds_read_b128 v[128:131], v238 offset:40960
	ds_read_b128 v[132:135], v238 offset:43008
	ds_read_b128 v[136:139], v238 offset:45056
	ds_read_b128 v[140:143], v238 offset:47104
	v_mfma_f32_16x16x32_bf16 v[184:187], v[88:91], v[74:77], v[184:187]
	ds_read_b128 v[144:147], v238 offset:33792
	ds_read_b128 v[148:151], v238 offset:35840
	ds_read_b128 v[152:155], v238 offset:37888
	ds_read_b128 v[156:159], v238 offset:39936
	v_mfma_f32_16x16x32_bf16 v[188:191], v[92:95], v[74:77], v[188:191]
	ds_read_b128 v[160:163], v238 offset:41984
	ds_read_b128 v[164:167], v238 offset:44032
	ds_read_b128 v[168:171], v238 offset:46080
	ds_read_b128 v[172:175], v238 offset:48128
	v_mfma_f32_16x16x32_bf16 v[196:199], v[74:77], v[96:99], v[196:199]
	v_sub_f32_e32 v212, v212, v176
	v_sub_f32_e32 v213, v213, v177
	v_sub_f32_e32 v214, v214, v178
	v_sub_f32_e32 v215, v215, v179
	v_mfma_f32_16x16x32_bf16 v[200:203], v[74:77], v[100:103], v[200:203]
	v_sub_f32_e32 v216, v216, v180
	v_sub_f32_e32 v217, v217, v181
	v_sub_f32_e32 v218, v218, v182
	v_sub_f32_e32 v219, v219, v183
	v_mfma_f32_16x16x32_bf16 v[204:207], v[74:77], v[104:107], v[204:207]
	v_sub_f32_e32 v220, v220, v184
	v_sub_f32_e32 v221, v221, v185
	v_sub_f32_e32 v222, v222, v186
	v_sub_f32_e32 v223, v223, v187
	v_mfma_f32_16x16x32_bf16 v[208:211], v[74:77], v[108:111], v[208:211]
	v_sub_f32_e32 v224, v224, v188
	v_sub_f32_e32 v225, v225, v189
	v_sub_f32_e32 v226, v226, v190
	v_sub_f32_e32 v227, v227, v191
	v_cvt_pk_bf16_f32 v228, v212, v213
	v_cvt_pk_bf16_f32 v229, v214, v215
	v_cvt_pk_bf16_f32 v230, v216, v217
	v_cvt_pk_bf16_f32 v231, v218, v219
	v_cvt_pk_bf16_f32 v232, v220, v221
	v_cvt_pk_bf16_f32 v233, v222, v223
	v_cvt_pk_bf16_f32 v234, v224, v225
	v_cvt_pk_bf16_f32 v235, v226, v227
	s_waitcnt lgkmcnt(8)
	s_nop 0
	v_mfma_f32_16x16x32_bf16 v[4:7], v[112:115], v[228:231], v[4:7]
	ds_read_b128 v[80:83], v238 offset:49152
	v_mfma_f32_16x16x32_bf16 v[8:11], v[116:119], v[228:231], v[8:11]
	ds_read_b128 v[84:87], v238 offset:51200
	v_mfma_f32_16x16x32_bf16 v[12:15], v[120:123], v[228:231], v[12:15]
	ds_read_b128 v[88:91], v238 offset:53248
	v_mfma_f32_16x16x32_bf16 v[16:19], v[124:127], v[228:231], v[16:19]
	ds_read_b128 v[92:95], v238 offset:55296
	v_mfma_f32_16x16x32_bf16 v[20:23], v[128:131], v[228:231], v[20:23]
	ds_read_b128 v[96:99], v238 offset:50176
	v_mfma_f32_16x16x32_bf16 v[24:27], v[132:135], v[228:231], v[24:27]
	ds_read_b128 v[100:103], v238 offset:52224
	v_mfma_f32_16x16x32_bf16 v[28:31], v[136:139], v[228:231], v[28:31]
	ds_read_b128 v[104:107], v238 offset:54272
	v_mfma_f32_16x16x32_bf16 v[32:35], v[140:143], v[228:231], v[32:35]
	ds_read_b128 v[108:111], v238 offset:56320
	s_waitcnt lgkmcnt(8)
	v_mfma_f32_16x16x32_bf16 v[4:7], v[144:147], v[232:235], v[4:7]
	v_mfma_f32_16x16x32_bf16 v[8:11], v[148:151], v[232:235], v[8:11]
	v_mfma_f32_16x16x32_bf16 v[12:15], v[152:155], v[232:235], v[12:15]
	v_mfma_f32_16x16x32_bf16 v[16:19], v[156:159], v[232:235], v[16:19]
	v_mfma_f32_16x16x32_bf16 v[20:23], v[160:163], v[232:235], v[20:23]
	v_mfma_f32_16x16x32_bf16 v[24:27], v[164:167], v[232:235], v[24:27]
	v_mfma_f32_16x16x32_bf16 v[28:31], v[168:171], v[232:235], v[28:31]
	v_mfma_f32_16x16x32_bf16 v[32:35], v[172:175], v[232:235], v[32:35]
	s_waitcnt lgkmcnt(0)
	v_mfma_f32_16x16x32_bf16 v[196:199], v[228:231], v[80:83], v[196:199]
	s_add_u32 s48, s48, 0x20000
	v_mfma_f32_16x16x32_bf16 v[200:203], v[228:231], v[84:87], v[200:203]
	s_addc_u32 s49, s49, 0
	v_mfma_f32_16x16x32_bf16 v[204:207], v[228:231], v[88:91], v[204:207]
	s_add_u32 s36, s36, 32
	v_mfma_f32_16x16x32_bf16 v[208:211], v[228:231], v[92:95], v[208:211]
	v_mfma_f32_16x16x32_bf16 v[196:199], v[232:235], v[96:99], v[196:199]
	s_addc_u32 s37, s37, 0
	v_mfma_f32_16x16x32_bf16 v[200:203], v[232:235], v[100:103], v[200:203]
	v_xor_b32_e32 v238, 0xe000, v238
	v_mfma_f32_16x16x32_bf16 v[204:207], v[232:235], v[104:107], v[204:207]
	s_add_i32 s19, s19, 1
	v_mfma_f32_16x16x32_bf16 v[208:211], v[232:235], v[108:111], v[208:211]
	s_nop 7
	v_cvt_pk_bf16_f32 v78, v196, v197
	v_cvt_pk_bf16_f32 v79, v198, v199
	v_cvt_pk_bf16_f32 v194, v200, v201
	v_cvt_pk_bf16_f32 v195, v202, v203
	v_cvt_pk_bf16_f32 v254, v204, v205
	v_cvt_pk_bf16_f32 v255, v206, v207
	v_cvt_pk_bf16_f32 v242, v208, v209
	v_cvt_pk_bf16_f32 v243, v210, v211
	s_cmp_lt_u32 s19, 32
	s_barrier
	s_cbranch_scc1 .Lg2c_loop
	global_store_dwordx2 v239, v[78:79], s[28:29]
	global_store_dwordx2 v240, v[194:195], s[28:29]
	global_store_dwordx2 v241, v[254:255], s[28:29]
	global_store_dwordx2 v246, v[242:243], s[28:29]
	s_add_u32 s28, s28, 0x20000
	s_addc_u32 s29, s29, 0
	s_branch .Lg2_exit
